# DeltaNet prep wave 5: per-head a_log and dt_bias read from a once-per-phase register table via v_readlane instead of two per-unit global loads with vmcnt(0)
# speedup vs baseline: 1.0293x; 1.0019x over previous
.LBB0_520:
	s_mov_b32 s36, s70
	s_mov_b32 s91, s55
	s_cmpk_gt_i32 s36, 0xfff
	v_readlane_b32 s51, v244, 10
	s_movk_i32 s70, 0xff
	s_cbranch_scc1 .LBB0_601
	s_add_u32 s40, s22, 0x1dc80000
	s_addc_u32 s41, s23, 0
	s_mul_i32 s8, s92, 0xc000
	s_mul_hi_i32 s2, s92, 0xc000
	s_add_u32 s42, s6, s8
	s_addc_u32 s43, s7, s2
	s_add_u32 s59, s22, 0x4000000
	s_addc_u32 s64, s23, 0
	s_lshl_b32 s74, s92, 3
	s_load_dwordx2 s[94:95], s[0:1], 0x48
	s_load_dwordx2 s[96:97], s[0:1], 0x50
	v_mbcnt_lo_u32_b32 v98, -1, 0
	v_mbcnt_hi_u32_b32 v98, -1, v98
	v_and_b32_e32 v98, 7, v98
	v_add_u32_e32 v98, s74, v98
	v_lshlrev_b32_e32 v98, 2, v98
	s_waitcnt lgkmcnt(0)
	global_load_dword v96, v98, s[94:95]
	global_load_dword v97, v98, s[96:97]
	s_add_u32 s26, s42, 0x1000
	s_addc_u32 s27, s43, 0
	s_add_u32 s75, s42, 0x3000
	s_addc_u32 s52, s43, 0
	s_add_u32 s28, s42, 0x4000
	s_addc_u32 s29, s43, 0
	s_add_u32 s53, s42, 0x6000
	s_addc_u32 s54, s43, 0
	s_add_u32 s30, s42, 0x7000
	s_addc_u32 s31, s43, 0
	s_add_u32 s55, s42, 0x9000
	s_addc_u32 s60, s43, 0
	s_add_u32 s34, s42, 0xa000
	s_addc_u32 s35, s43, 0
	s_lshl_b32 s61, s36, 6
	s_branch .LBB0_524

.LBB0_524:
	v_mov_b32_e32 v80, v68
	s_bfe_u32 s16, s36, 0x30006
	v_lshlrev_b32_e32 v0, 2, v80
	v_and_b32_e32 v42, 0xfffffc00, v0
	v_ashrrev_i32_e32 v43, 31, v42
	v_lshlrev_b64 v[14:15], 2, v[42:43]
	v_and_b32_e32 v85, 31, v80
	s_lshl_b32 s62, s16, 9
	v_lshl_add_u64 v[6:7], s[28:29], 0, v[14:15]
	v_lshl_add_u64 v[2:3], s[26:27], 0, v[14:15]
	v_lshlrev_b32_e32 v0, 4, v85
	v_lshl_add_u64 v[6:7], v[6:7], 0, s[62:63]
	v_lshl_add_u64 v[2:3], v[2:3], 0, s[62:63]
	v_lshl_add_u64 v[6:7], v[6:7], 0, v[0:1]
	v_lshl_add_u64 v[10:11], s[30:31], 0, v[14:15]
	v_lshl_add_u64 v[2:3], v[2:3], 0, v[0:1]
	global_load_dwordx4 v[6:9], v[6:7], off
	v_lshl_add_u64 v[10:11], v[10:11], 0, s[62:63]
	v_lshl_add_u64 v[14:15], s[34:35], 0, v[14:15]
	global_load_dwordx4 v[2:5], v[2:3], off
	v_lshl_add_u64 v[10:11], v[10:11], 0, v[0:1]
	v_lshl_add_u64 v[14:15], v[14:15], 0, s[62:63]
	global_load_dwordx4 v[10:13], v[10:11], off
	v_lshl_add_u64 v[14:15], v[14:15], 0, v[0:1]
	global_load_dwordx4 v[14:17], v[14:15], off
	s_ashr_i32 s37, s36, 31
	v_and_b32_e32 v81, 63, v80
	s_add_u32 s6, s42, s62
	s_addc_u32 s7, s43, 0
	v_lshlrev_b32_e32 v43, 3, v81
	global_load_dwordx2 v[44:45], v43, s[6:7]
	s_add_u32 s6, s75, s62
	s_addc_u32 s7, s52, 0
	global_load_dwordx2 v[46:47], v43, s[6:7]
	s_add_u32 s6, s53, s62
	s_waitcnt vmcnt(14)
	v_lshlrev_b32_e32 v64, 16, v18
	v_and_b32_e32 v65, 0xffff0000, v18
	s_addc_u32 s7, s54, 0
	v_lshlrev_b32_e32 v56, 16, v20
	v_and_b32_e32 v57, 0xffff0000, v20
	global_load_dwordx2 v[48:49], v43, s[6:7]
	s_add_u32 s6, s55, s62
	v_lshlrev_b32_e32 v60, 16, v22
	v_and_b32_e32 v61, 0xffff0000, v22
	s_addc_u32 s7, s60, 0
	s_waitcnt vmcnt(14)
	v_lshlrev_b32_e32 v52, 16, v24
	v_and_b32_e32 v53, 0xffff0000, v24
	global_load_dwordx2 v[50:51], v43, s[6:7]
	v_lshlrev_b32_e32 v66, 16, v19
	v_and_b32_e32 v67, 0xffff0000, v19
	v_lshlrev_b32_e32 v58, 16, v21
	v_and_b32_e32 v59, 0xffff0000, v21
	v_lshlrev_b32_e32 v62, 16, v23
	v_and_b32_e32 v63, 0xffff0000, v23
	v_lshlrev_b32_e32 v54, 16, v25
	v_and_b32_e32 v55, 0xffff0000, v25
	s_movk_i32 s2, 0x100
	v_lshrrev_b32_e32 v84, 2, v80
	v_cmp_gt_u32_e64 s[8:9], s2, v80
	s_add_i32 s2, 0, 0x16000
	v_and_b32_e32 v82, 56, v84
	v_mov_b32_e32 v0, s2
	v_cndmask_b32_e64 v0, v0, 0, s[8:9]
	v_lshlrev_b32_e32 v86, 3, v85
	s_barrier
	v_ashrrev_i32_e32 v43, 6, v80
	v_cmp_lt_u32_e32 vcc, s70, v80
	s_waitcnt vmcnt(7)
	v_pk_mul_f32 v[88:89], v[6:7], v[64:65]
	v_pk_mul_f32 v[90:91], v[8:9], v[66:67]
	s_waitcnt vmcnt(6)
	v_pk_fma_f32 v[56:57], v[2:3], v[56:57], v[88:89]
	v_pk_fma_f32 v[58:59], v[4:5], v[58:59], v[90:91]
	v_pk_mul_f32 v[90:91], v[8:9], v[62:63]
	s_waitcnt vmcnt(5)
	v_pk_fma_f32 v[56:57], v[10:11], v[60:61], v[56:57]
	v_pk_fma_f32 v[58:59], v[12:13], v[62:63], v[58:59]
	s_waitcnt vmcnt(4)
	v_pk_fma_f32 v[56:57], v[14:15], v[52:53], v[56:57]
	v_pk_fma_f32 v[58:59], v[16:17], v[54:55], v[58:59]
	v_mul_f32_e32 v83, 0xbfb8aa3b, v56
	v_exp_f32_e32 v83, v83
	v_pk_fma_f32 v[66:67], v[4:5], v[66:67], v[90:91]
	v_pk_mul_f32 v[90:91], v[8:9], v[54:55]
	v_pk_fma_f32 v[66:67], v[12:13], v[54:55], v[66:67]
	v_add_f32_e32 v83, 1.0, v83
	v_rcp_f32_e32 v88, v83
	v_mul_f32_e32 v83, 0xbfb8aa3b, v57
	v_exp_f32_e32 v83, v83
	v_pk_fma_f32 v[62:63], v[4:5], v[62:63], v[90:91]
	v_add_f32_e32 v83, 1.0, v83
	v_rcp_f32_e32 v89, v83
	v_or_b32_e32 v83, 3, v82
	v_pk_mul_f32 v[56:57], v[56:57], v[88:89]
	s_nop 0
	v_cvt_pk_bf16_f32 v56, v56, v57
	v_mul_f32_e32 v57, 0xbfb8aa3b, v58
	v_exp_f32_e32 v57, v57
	s_nop 0
	v_add_f32_e32 v57, 1.0, v57
	v_rcp_f32_e32 v88, v57
	v_mul_f32_e32 v57, 0xbfb8aa3b, v59
	v_exp_f32_e32 v57, v57
	s_nop 0
	v_add_f32_e32 v57, 1.0, v57
	v_rcp_f32_e32 v89, v57
	s_nop 0
	v_pk_mul_f32 v[58:59], v[58:59], v[88:89]
	s_nop 0
	v_cvt_pk_bf16_f32 v57, v58, v59
	v_mul_u32_u24_e32 v58, 0x110, v83
	v_add3_u32 v87, v0, v58, v86
	v_pk_mul_f32 v[88:89], v[6:7], v[60:61]
	v_add_u32_e32 v58, 0xfffffcd0, v87
	v_pk_fma_f32 v[64:65], v[2:3], v[64:65], v[88:89]
	ds_write_b64 v58, v[56:57]
	v_lshlrev_b32_e32 v56, 16, v26
	v_and_b32_e32 v57, 0xffff0000, v26
	v_pk_fma_f32 v[64:65], v[10:11], v[52:53], v[64:65]
	v_lshlrev_b32_e32 v58, 16, v27
	v_pk_fma_f32 v[64:65], v[14:15], v[56:57], v[64:65]
	v_and_b32_e32 v59, 0xffff0000, v27
	v_mul_f32_e32 v88, 0xbfb8aa3b, v64
	v_mul_f32_e32 v89, 0xbfb8aa3b, v65
	v_exp_f32_e32 v88, v88
	v_exp_f32_e32 v89, v89
	v_pk_fma_f32 v[66:67], v[16:17], v[58:59], v[66:67]
	v_pk_fma_f32 v[62:63], v[12:13], v[58:59], v[62:63]
	v_add_f32_e32 v88, 1.0, v88
	v_add_f32_e32 v89, 1.0, v89
	v_rcp_f32_e32 v88, v88
	v_rcp_f32_e32 v89, v89
	v_pk_mul_f32 v[90:91], v[8:9], v[58:59]
	v_pk_mul_f32 v[64:65], v[64:65], v[88:89]
	s_nop 0
	v_cvt_pk_bf16_f32 v64, v64, v65
	v_mul_f32_e32 v65, 0xbfb8aa3b, v66
	v_exp_f32_e32 v65, v65
	v_pk_fma_f32 v[54:55], v[4:5], v[54:55], v[90:91]
	v_add_f32_e32 v65, 1.0, v65
	v_rcp_f32_e32 v88, v65
	v_mul_f32_e32 v65, 0xbfb8aa3b, v67
	v_exp_f32_e32 v65, v65
	s_nop 0
	v_add_f32_e32 v65, 1.0, v65
	v_rcp_f32_e32 v89, v65
	s_nop 0
	v_pk_mul_f32 v[66:67], v[66:67], v[88:89]
	v_pk_mul_f32 v[88:89], v[6:7], v[52:53]
	v_cvt_pk_bf16_f32 v65, v66, v67
	v_add_u32_e32 v66, 0xfffffde0, v87
	v_pk_fma_f32 v[60:61], v[2:3], v[60:61], v[88:89]
	ds_write_b64 v66, v[64:65]
	v_lshlrev_b32_e32 v64, 16, v28
	v_and_b32_e32 v65, 0xffff0000, v28
	v_pk_fma_f32 v[60:61], v[10:11], v[56:57], v[60:61]
	v_lshlrev_b32_e32 v66, 16, v29
	v_pk_fma_f32 v[60:61], v[14:15], v[64:65], v[60:61]
	v_and_b32_e32 v67, 0xffff0000, v29
	v_mul_f32_e32 v88, 0xbfb8aa3b, v60
	v_mul_f32_e32 v89, 0xbfb8aa3b, v61
	v_exp_f32_e32 v88, v88
	v_exp_f32_e32 v89, v89
	v_pk_fma_f32 v[62:63], v[16:17], v[66:67], v[62:63]
	v_pk_fma_f32 v[54:55], v[12:13], v[66:67], v[54:55]
	v_add_f32_e32 v88, 1.0, v88
	v_add_f32_e32 v89, 1.0, v89
	v_rcp_f32_e32 v88, v88
	v_rcp_f32_e32 v89, v89
	v_pk_mul_f32 v[90:91], v[6:7], v[64:65]
	v_pk_mul_f32 v[92:93], v[8:9], v[66:67]
	v_pk_mul_f32 v[60:61], v[60:61], v[88:89]
	s_nop 0
	v_cvt_pk_bf16_f32 v60, v60, v61
	v_mul_f32_e32 v61, 0xbfb8aa3b, v62
	v_exp_f32_e32 v61, v61
	v_pk_fma_f32 v[58:59], v[4:5], v[58:59], v[92:93]
	v_add_f32_e32 v61, 1.0, v61
	v_rcp_f32_e32 v88, v61
	v_mul_f32_e32 v61, 0xbfb8aa3b, v63
	v_exp_f32_e32 v61, v61
	s_nop 0
	v_add_f32_e32 v61, 1.0, v61
	v_rcp_f32_e32 v89, v61
	s_nop 0
	v_pk_mul_f32 v[62:63], v[62:63], v[88:89]
	v_pk_mul_f32 v[88:89], v[6:7], v[56:57]
	v_cvt_pk_bf16_f32 v61, v62, v63
	v_add_u32_e32 v62, 0xfffffef0, v87
	v_pk_fma_f32 v[52:53], v[2:3], v[52:53], v[88:89]
	ds_write_b64 v62, v[60:61]
	v_lshlrev_b32_e32 v60, 16, v30
	v_and_b32_e32 v61, 0xffff0000, v30
	v_pk_fma_f32 v[52:53], v[10:11], v[64:65], v[52:53]
	v_lshlrev_b32_e32 v62, 16, v31
	v_pk_fma_f32 v[52:53], v[14:15], v[60:61], v[52:53]
	v_and_b32_e32 v63, 0xffff0000, v31
	v_mul_f32_e32 v88, 0xbfb8aa3b, v52
	v_mul_f32_e32 v89, 0xbfb8aa3b, v53
	v_exp_f32_e32 v88, v88
	v_exp_f32_e32 v89, v89
	v_pk_fma_f32 v[54:55], v[16:17], v[62:63], v[54:55]
	v_pk_fma_f32 v[56:57], v[2:3], v[56:57], v[90:91]
	v_add_f32_e32 v88, 1.0, v88
	v_add_f32_e32 v89, 1.0, v89
	v_rcp_f32_e32 v88, v88
	v_rcp_f32_e32 v89, v89
	v_pk_fma_f32 v[56:57], v[10:11], v[60:61], v[56:57]
	v_pk_fma_f32 v[58:59], v[12:13], v[62:63], v[58:59]
	v_pk_mul_f32 v[52:53], v[52:53], v[88:89]
	s_nop 0
	v_cvt_pk_bf16_f32 v88, v52, v53
	v_mul_f32_e32 v52, 0xbfb8aa3b, v54
	v_mul_f32_e32 v53, 0xbfb8aa3b, v55
	v_exp_f32_e32 v52, v52
	v_exp_f32_e32 v53, v53
	v_add_f32_e32 v52, 1.0, v52
	v_add_f32_e32 v53, 1.0, v53
	v_rcp_f32_e32 v52, v52
	v_rcp_f32_e32 v53, v53
	s_nop 0
	v_pk_mul_f32 v[52:53], v[54:55], v[52:53]
	s_nop 0
	v_cvt_pk_bf16_f32 v89, v52, v53
	v_lshlrev_b32_e32 v52, 16, v32
	v_and_b32_e32 v53, 0xffff0000, v32
	v_pk_fma_f32 v[56:57], v[14:15], v[52:53], v[56:57]
	v_lshlrev_b32_e32 v54, 16, v33
	v_mul_f32_e32 v90, 0xbfb8aa3b, v56
	v_mul_f32_e32 v91, 0xbfb8aa3b, v57
	v_exp_f32_e32 v90, v90
	v_exp_f32_e32 v91, v91
	v_and_b32_e32 v55, 0xffff0000, v33
	v_pk_fma_f32 v[58:59], v[16:17], v[54:55], v[58:59]
	v_add_f32_e32 v90, 1.0, v90
	v_add_f32_e32 v91, 1.0, v91
	v_rcp_f32_e32 v90, v90
	v_rcp_f32_e32 v91, v91
	s_nop 0
	v_pk_mul_f32 v[56:57], v[56:57], v[90:91]
	s_nop 0
	v_cvt_pk_bf16_f32 v56, v56, v57
	v_mul_f32_e32 v57, 0xbfb8aa3b, v58
	v_exp_f32_e32 v57, v57
	s_nop 0
	v_add_f32_e32 v57, 1.0, v57
	v_rcp_f32_e32 v90, v57
	v_mul_f32_e32 v57, 0xbfb8aa3b, v59
	v_exp_f32_e32 v57, v57
	s_nop 0
	v_add_f32_e32 v57, 1.0, v57
	v_rcp_f32_e32 v91, v57
	s_nop 0
	v_pk_mul_f32 v[58:59], v[58:59], v[90:91]
	s_nop 0
	v_cvt_pk_bf16_f32 v57, v58, v59
	ds_write2_b64 v87, v[88:89], v[56:57] offset1:34
	v_pk_mul_f32 v[88:89], v[6:7], v[60:61]
	v_lshlrev_b32_e32 v56, 16, v34
	v_pk_fma_f32 v[64:65], v[2:3], v[64:65], v[88:89]
	v_and_b32_e32 v57, 0xffff0000, v34
	v_pk_fma_f32 v[64:65], v[10:11], v[52:53], v[64:65]
	v_pk_mul_f32 v[90:91], v[8:9], v[62:63]
	v_pk_fma_f32 v[64:65], v[14:15], v[56:57], v[64:65]
	v_pk_fma_f32 v[66:67], v[4:5], v[66:67], v[90:91]
	v_mul_f32_e32 v87, 0xbfb8aa3b, v64
	v_exp_f32_e32 v87, v87
	v_lshlrev_b32_e32 v58, 16, v35
	v_and_b32_e32 v59, 0xffff0000, v35
	v_pk_fma_f32 v[66:67], v[12:13], v[54:55], v[66:67]
	v_add_f32_e32 v87, 1.0, v87
	v_rcp_f32_e32 v88, v87
	v_mul_f32_e32 v87, 0xbfb8aa3b, v65
	v_exp_f32_e32 v87, v87
	v_pk_fma_f32 v[66:67], v[16:17], v[58:59], v[66:67]
	v_pk_mul_f32 v[90:91], v[8:9], v[54:55]
	v_pk_mul_f32 v[8:9], v[8:9], v[58:59]
	v_add_f32_e32 v87, 1.0, v87
	v_rcp_f32_e32 v89, v87
	v_pk_fma_f32 v[62:63], v[4:5], v[62:63], v[90:91]
	v_and_b32_e32 v87, 0xffff0000, v37
	v_pk_fma_f32 v[62:63], v[12:13], v[58:59], v[62:63]
	v_pk_mul_f32 v[64:65], v[64:65], v[88:89]
	v_pk_fma_f32 v[4:5], v[4:5], v[54:55], v[8:9]
	v_cvt_pk_bf16_f32 v64, v64, v65
	v_mul_f32_e32 v65, 0xbfb8aa3b, v66
	v_exp_f32_e32 v65, v65
	s_nop 0
	v_add_f32_e32 v65, 1.0, v65
	v_rcp_f32_e32 v88, v65
	v_mul_f32_e32 v65, 0xbfb8aa3b, v67
	v_exp_f32_e32 v65, v65
	s_nop 0
	v_add_f32_e32 v65, 1.0, v65
	v_rcp_f32_e32 v89, v65
	s_nop 0
	v_pk_mul_f32 v[66:67], v[66:67], v[88:89]
	v_pk_mul_f32 v[88:89], v[6:7], v[52:53]
	v_cvt_pk_bf16_f32 v65, v66, v67
	v_mul_u32_u24_e32 v66, 0x110, v82
	v_pk_fma_f32 v[60:61], v[2:3], v[60:61], v[88:89]
	v_add3_u32 v0, v0, v66, v86
	v_lshlrev_b32_e32 v66, 16, v36
	v_and_b32_e32 v67, 0xffff0000, v36
	v_pk_fma_f32 v[60:61], v[10:11], v[56:57], v[60:61]
	v_lshlrev_b32_e32 v86, 16, v37
	v_pk_fma_f32 v[60:61], v[14:15], v[66:67], v[60:61]
	v_pk_fma_f32 v[62:63], v[16:17], v[86:87], v[62:63]
	v_mul_f32_e32 v88, 0xbfb8aa3b, v60
	v_mul_f32_e32 v89, 0xbfb8aa3b, v61
	v_exp_f32_e32 v88, v88
	v_exp_f32_e32 v89, v89
	v_pk_mul_f32 v[6:7], v[6:7], v[56:57]
	v_pk_fma_f32 v[4:5], v[12:13], v[86:87], v[4:5]
	v_add_f32_e32 v88, 1.0, v88
	v_add_f32_e32 v89, 1.0, v89
	v_rcp_f32_e32 v88, v88
	v_rcp_f32_e32 v89, v89
	v_pk_fma_f32 v[2:3], v[2:3], v[52:53], v[6:7]
	v_pk_mul_f32 v[60:61], v[60:61], v[88:89]
	s_nop 0
	v_cvt_pk_bf16_f32 v60, v60, v61
	v_mul_f32_e32 v61, 0xbfb8aa3b, v62
	v_exp_f32_e32 v61, v61
	v_pk_fma_f32 v[2:3], v[10:11], v[66:67], v[2:3]
	v_add_f32_e32 v61, 1.0, v61
	v_rcp_f32_e32 v88, v61
	v_mul_f32_e32 v61, 0xbfb8aa3b, v63
	v_exp_f32_e32 v61, v61
	s_nop 0
	v_add_f32_e32 v61, 1.0, v61
	v_rcp_f32_e32 v89, v61
	s_nop 0
	v_pk_mul_f32 v[62:63], v[62:63], v[88:89]
	s_nop 0
	v_cvt_pk_bf16_f32 v61, v62, v63
	ds_write2_b64 v0, v[64:65], v[60:61] offset0:170 offset1:204
	v_lshlrev_b32_e32 v60, 16, v38
	v_and_b32_e32 v61, 0xffff0000, v38
	v_pk_fma_f32 v[2:3], v[14:15], v[60:61], v[2:3]
	v_lshlrev_b32_e32 v62, 16, v39
	v_mul_f32_e32 v6, 0xbfb8aa3b, v2
	v_mul_f32_e32 v7, 0xbfb8aa3b, v3
	v_exp_f32_e32 v6, v6
	v_exp_f32_e32 v7, v7
	v_and_b32_e32 v63, 0xffff0000, v39
	v_pk_fma_f32 v[4:5], v[16:17], v[62:63], v[4:5]
	v_add_f32_e32 v6, 1.0, v6
	v_add_f32_e32 v7, 1.0, v7
	v_rcp_f32_e32 v6, v6
	v_rcp_f32_e32 v7, v7
	s_nop 0
	v_pk_mul_f32 v[2:3], v[2:3], v[6:7]
	s_nop 0
	v_cvt_pk_bf16_f32 v2, v2, v3
	v_mul_f32_e32 v3, 0xbfb8aa3b, v4
	v_exp_f32_e32 v3, v3
	s_nop 0
	v_add_f32_e32 v3, 1.0, v3
	v_rcp_f32_e32 v6, v3
	v_mul_f32_e32 v3, 0xbfb8aa3b, v5
	v_exp_f32_e32 v3, v3
	s_nop 0
	v_add_f32_e32 v3, 1.0, v3
	v_rcp_f32_e32 v7, v3
	s_nop 0
	v_pk_mul_f32 v[4:5], v[4:5], v[6:7]
	s_nop 0
	v_cvt_pk_bf16_f32 v3, v4, v5
	ds_write_b64 v0, v[2:3] offset:1904
	v_lshlrev_b32_e32 v4, 16, v69
	v_and_b32_e32 v5, 0xffff0000, v69
	v_lshlrev_b32_e32 v2, 16, v70
	v_and_b32_e32 v3, 0xffff0000, v70
	s_waitcnt vmcnt(2)
	v_pk_mul_f32 v[12:13], v[46:47], v[4:5]
	v_lshlrev_b32_e32 v6, 16, v72
	v_and_b32_e32 v7, 0xffff0000, v72
	v_pk_fma_f32 v[2:3], v[44:45], v[2:3], v[12:13]
	v_lshlrev_b32_e32 v8, 16, v71
	v_and_b32_e32 v9, 0xffff0000, v71
	s_waitcnt vmcnt(1)
	v_pk_fma_f32 v[2:3], v[48:49], v[6:7], v[2:3]
	v_lshlrev_b32_e32 v10, 3, v43
	s_waitcnt vmcnt(0)
	v_pk_fma_f32 v[2:3], v[50:51], v[8:9], v[2:3]
	s_movk_i32 s6, 0x110
	v_mul_f32_e32 v11, 0xbfb8aa3b, v2
	v_exp_f32_e32 v11, v11
	v_lshlrev_b32_e32 v0, 2, v81
	v_pk_mul_f32 v[14:15], v[46:47], v[6:7]
	s_movk_i32 s7, 0x880
	v_add_f32_e32 v11, 1.0, v11
	v_rcp_f32_e32 v12, v11
	v_mul_f32_e32 v11, 0xbfb8aa3b, v3
	v_exp_f32_e32 v11, v11
	v_pk_fma_f32 v[4:5], v[44:45], v[4:5], v[14:15]
	v_add_f32_e32 v11, 1.0, v11
	v_rcp_f32_e32 v13, v11
	v_pk_fma_f32 v[4:5], v[48:49], v[8:9], v[4:5]
	v_pk_mul_f32 v[2:3], v[2:3], v[12:13]
	v_or_b32_e32 v12, 3, v10
	v_cvt_pk_bf16_f32 v2, v2, v3
	v_mul_lo_u32 v3, v12, s6
	v_readlane_b32 s6, v244, 12
	s_nop 1
	v_add3_u32 v11, s6, v3, v0
	v_add_u32_e32 v3, 0xfffffcd0, v11
	ds_write_b32 v3, v2
	v_lshlrev_b32_e32 v2, 16, v74
	v_and_b32_e32 v3, 0xffff0000, v74
	v_pk_fma_f32 v[4:5], v[50:51], v[2:3], v[4:5]
	s_nop 0
	v_mul_f32_e32 v13, 0xbfb8aa3b, v4
	v_exp_f32_e32 v13, v13
	s_nop 0
	v_add_f32_e32 v13, 1.0, v13
	v_rcp_f32_e32 v14, v13
	v_mul_f32_e32 v13, 0xbfb8aa3b, v5
	v_exp_f32_e32 v13, v13
	s_nop 0
	v_add_f32_e32 v13, 1.0, v13
	v_rcp_f32_e32 v15, v13
	s_nop 0
	v_pk_mul_f32 v[4:5], v[4:5], v[14:15]
	v_pk_mul_f32 v[14:15], v[46:47], v[8:9]
	v_cvt_pk_bf16_f32 v4, v4, v5
	v_add_u32_e32 v5, 0xfffffde0, v11
	v_pk_fma_f32 v[6:7], v[44:45], v[6:7], v[14:15]
	ds_write_b32 v5, v4
	v_lshlrev_b32_e32 v4, 16, v73
	v_and_b32_e32 v5, 0xffff0000, v73
	v_pk_fma_f32 v[6:7], v[48:49], v[2:3], v[6:7]
	s_nop 0
	v_pk_fma_f32 v[6:7], v[50:51], v[4:5], v[6:7]
	s_nop 0
	v_mul_f32_e32 v13, 0xbfb8aa3b, v6
	v_exp_f32_e32 v13, v13
	s_nop 0
	v_add_f32_e32 v13, 1.0, v13
	v_rcp_f32_e32 v14, v13
	v_mul_f32_e32 v13, 0xbfb8aa3b, v7
	v_exp_f32_e32 v13, v13
	s_nop 0
	v_add_f32_e32 v13, 1.0, v13
	v_rcp_f32_e32 v15, v13
	s_nop 0
	v_pk_mul_f32 v[6:7], v[6:7], v[14:15]
	v_pk_mul_f32 v[14:15], v[46:47], v[2:3]
	v_cvt_pk_bf16_f32 v6, v6, v7
	v_add_u32_e32 v7, 0xfffffef0, v11
	v_pk_fma_f32 v[8:9], v[44:45], v[8:9], v[14:15]
	ds_write_b32 v7, v6
	v_lshlrev_b32_e32 v6, 16, v76
	v_and_b32_e32 v7, 0xffff0000, v76
	v_pk_fma_f32 v[8:9], v[48:49], v[4:5], v[8:9]
	s_nop 0
	v_pk_fma_f32 v[8:9], v[50:51], v[6:7], v[8:9]
	s_nop 0
	v_mul_f32_e32 v13, 0xbfb8aa3b, v8
	v_exp_f32_e32 v13, v13
	s_nop 0
	v_add_f32_e32 v13, 1.0, v13
	v_rcp_f32_e32 v14, v13
	v_mul_f32_e32 v13, 0xbfb8aa3b, v9
	v_exp_f32_e32 v13, v13
	s_nop 0
	v_add_f32_e32 v13, 1.0, v13
	v_rcp_f32_e32 v15, v13
	s_nop 0
	v_pk_mul_f32 v[8:9], v[8:9], v[14:15]
	v_pk_mul_f32 v[14:15], v[46:47], v[4:5]
	v_cvt_pk_bf16_f32 v13, v8, v9
	v_pk_fma_f32 v[2:3], v[44:45], v[2:3], v[14:15]
	v_lshlrev_b32_e32 v8, 16, v75
	v_and_b32_e32 v9, 0xffff0000, v75
	v_pk_fma_f32 v[2:3], v[48:49], v[6:7], v[2:3]
	s_nop 0
	v_pk_fma_f32 v[2:3], v[50:51], v[8:9], v[2:3]
	s_nop 0
	v_mul_f32_e32 v14, 0xbfb8aa3b, v2
	v_mul_f32_e32 v15, 0xbfb8aa3b, v3
	v_exp_f32_e32 v14, v14
	v_exp_f32_e32 v15, v15
	v_add_f32_e32 v14, 1.0, v14
	v_add_f32_e32 v15, 1.0, v15
	v_rcp_f32_e32 v14, v14
	v_rcp_f32_e32 v15, v15
	s_nop 0
	v_pk_mul_f32 v[2:3], v[2:3], v[14:15]
	v_pk_mul_f32 v[14:15], v[46:47], v[6:7]
	v_cvt_pk_bf16_f32 v2, v2, v3
	v_pk_fma_f32 v[4:5], v[44:45], v[4:5], v[14:15]
	ds_write2_b32 v11, v13, v2 offset1:68
	v_lshlrev_b32_e32 v2, 16, v78
	v_and_b32_e32 v3, 0xffff0000, v78
	v_pk_fma_f32 v[4:5], v[48:49], v[8:9], v[4:5]
	s_nop 0
	v_pk_fma_f32 v[4:5], v[50:51], v[2:3], v[4:5]
	s_nop 0
	v_mul_f32_e32 v11, 0xbfb8aa3b, v4
	v_exp_f32_e32 v11, v11
	s_nop 0
	v_add_f32_e32 v11, 1.0, v11
	v_rcp_f32_e32 v14, v11
	v_mul_f32_e32 v11, 0xbfb8aa3b, v5
	v_exp_f32_e32 v11, v11
	s_nop 0
	v_add_f32_e32 v11, 1.0, v11
	v_rcp_f32_e32 v15, v11
	s_nop 0
	v_pk_mul_f32 v[4:5], v[4:5], v[14:15]
	v_pk_mul_f32 v[14:15], v[46:47], v[8:9]
	v_cvt_pk_bf16_f32 v11, v4, v5
	v_mul_lo_u32 v4, v43, s7
	v_pk_fma_f32 v[6:7], v[44:45], v[6:7], v[14:15]
	v_add3_u32 v0, s6, v4, v0
	v_lshlrev_b32_e32 v4, 16, v77
	v_and_b32_e32 v5, 0xffff0000, v77
	v_pk_fma_f32 v[6:7], v[48:49], v[2:3], v[6:7]
	v_pk_mul_f32 v[2:3], v[46:47], v[2:3]
	v_pk_fma_f32 v[6:7], v[50:51], v[4:5], v[6:7]
	v_pk_fma_f32 v[2:3], v[44:45], v[8:9], v[2:3]
	v_mul_f32_e32 v13, 0xbfb8aa3b, v6
	v_exp_f32_e32 v13, v13
	v_pk_fma_f32 v[2:3], v[48:49], v[4:5], v[2:3]
	v_cmp_eq_u32_e64 s[6:7], 5, v43
	v_add_f32_e32 v13, 1.0, v13
	v_rcp_f32_e32 v14, v13
	v_mul_f32_e32 v13, 0xbfb8aa3b, v7
	v_exp_f32_e32 v13, v13
	s_nop 0
	v_add_f32_e32 v13, 1.0, v13
	v_rcp_f32_e32 v15, v13
	s_nop 0
	v_pk_mul_f32 v[6:7], v[6:7], v[14:15]
	s_nop 0
	v_cvt_pk_bf16_f32 v6, v6, v7
	v_add_u32_e32 v7, 0x400, v0
	ds_write2_b32 v7, v11, v6 offset0:84 offset1:152
	v_lshlrev_b32_e32 v6, 16, v79
	v_and_b32_e32 v7, 0xffff0000, v79
	v_pk_fma_f32 v[2:3], v[50:51], v[6:7], v[2:3]
	s_nop 0
	v_mul_f32_e32 v4, 0xbfb8aa3b, v2
	v_mul_f32_e32 v5, 0xbfb8aa3b, v3
	v_exp_f32_e32 v4, v4
	v_exp_f32_e32 v5, v5
	v_add_f32_e32 v4, 1.0, v4
	v_add_f32_e32 v5, 1.0, v5
	v_rcp_f32_e32 v4, v4
	v_rcp_f32_e32 v5, v5
	s_nop 0
	v_pk_mul_f32 v[2:3], v[2:3], v[4:5]
	s_nop 0
	v_cvt_pk_bf16_f32 v2, v2, v3
	ds_write_b32 v0, v2 offset:1904
	s_and_saveexec_b64 s[12:13], s[6:7]
	s_cbranch_execz .LBB0_529
	s_waitcnt vmcnt(0) lgkmcnt(0)
	v_readlane_b32 s14, v96, s16
	v_readlane_b32 s15, v97, s16
	s_mov_b32 s10, 0x41a00000
	v_lshlrev_b32_e32 v40, 16, v40
	s_nop 0
	v_mov_b32_e32 v0, s14
	v_add_f32_e32 v2, s15, v40
	v_cmp_nlt_f32_e64 s[10:11], s10, v2
	s_and_saveexec_b64 s[14:15], s[10:11]
	s_cbranch_execz .LBB0_527
	v_mul_f32_e32 v2, 0x3fb8aa3b, v2
	v_exp_f32_e32 v11, v2
	s_mov_b32 s10, 0x3f2aaaab
	v_add_f32_e32 v4, 1.0, v11
	v_frexp_mant_f32_e32 v6, v4
	v_cvt_f64_f32_e32 v[2:3], v4
	v_frexp_exp_i32_f64_e32 v2, v[2:3]
	v_cmp_gt_f32_e64 s[10:11], s10, v6
	v_add_f32_e32 v5, -1.0, v4
	v_sub_f32_e32 v7, v5, v4
	v_subbrev_co_u32_e64 v13, s[10:11], 0, v2, s[10:11]
	v_sub_u32_e32 v2, 0, v13
	v_sub_f32_e32 v5, v11, v5
	v_add_f32_e32 v7, 1.0, v7
	v_ldexp_f32 v3, v4, v2
	v_add_f32_e32 v5, v5, v7
	v_add_f32_e32 v4, -1.0, v3
	v_add_f32_e32 v6, 1.0, v3
	v_ldexp_f32 v2, v5, v2
	v_add_f32_e32 v5, 1.0, v4
	v_add_f32_e32 v7, -1.0, v6
	v_sub_f32_e32 v5, v3, v5
	v_sub_f32_e32 v3, v3, v7
	v_add_f32_e32 v5, v2, v5
	v_add_f32_e32 v2, v2, v3
	v_add_f32_e32 v14, v6, v2
	v_rcp_f32_e32 v16, v14
	v_sub_f32_e32 v3, v14, v6
	v_sub_f32_e32 v15, v2, v3
	v_add_f32_e32 v3, v4, v5
	v_mul_f32_e32 v44, v3, v16
	v_sub_f32_e32 v2, v3, v4
	v_mul_f32_e32 v4, v14, v44
	v_fma_f32 v6, v44, v14, -v4
	v_fmac_f32_e32 v6, v44, v15
	v_sub_f32_e32 v17, v5, v2
	v_add_f32_e32 v2, v4, v6
	v_sub_f32_e32 v5, v3, v2
	v_pk_add_f32 v[8:9], v[2:3], v[4:5] neg_lo:[0,1] neg_hi:[0,1]
	v_mov_b32_e32 v7, v2
	v_pk_add_f32 v[2:3], v[8:9], v[6:7] neg_lo:[0,1] neg_hi:[0,1]
	s_mov_b32 s10, 0x3f317218
	v_add_f32_e32 v3, v17, v3
	v_add_f32_e32 v2, v2, v3
	v_add_f32_e32 v3, v5, v2
	v_mul_f32_e32 v17, v16, v3
	v_mul_f32_e32 v4, v14, v17
	v_fma_f32 v6, v17, v14, -v4
	v_fmac_f32_e32 v6, v17, v15
	v_sub_f32_e32 v5, v5, v3
	v_add_f32_e32 v14, v2, v5
	v_add_f32_e32 v2, v4, v6
	v_sub_f32_e32 v5, v3, v2
	v_pk_add_f32 v[8:9], v[2:3], v[4:5] neg_lo:[0,1] neg_hi:[0,1]
	v_mov_b32_e32 v7, v2
	v_pk_add_f32 v[2:3], v[8:9], v[6:7] neg_lo:[0,1] neg_hi:[0,1]
	s_nop 0
	v_add_f32_e32 v3, v14, v3
	v_add_f32_e32 v2, v2, v3
	v_add_f32_e32 v3, v44, v17
	v_add_f32_e32 v2, v5, v2
	v_sub_f32_e32 v4, v3, v44
	v_mul_f32_e32 v2, v16, v2
	v_sub_f32_e32 v4, v17, v4
	v_add_f32_e32 v4, v4, v2
	v_add_f32_e32 v6, v3, v4
	v_mul_f32_e32 v7, v6, v6
	v_fmamk_f32 v2, v7, 0x3e9b6dac, v162
	v_fmaak_f32 v145, v7, v2, 0x3f2aaada
	v_cvt_f32_i32_e32 v2, v13
	v_sub_f32_e32 v3, v6, v3
	v_sub_f32_e32 v3, v4, v3
	v_ldexp_f32 v8, v3, 1
	v_mul_f32_e32 v3, v6, v7
	v_ldexp_f32 v5, v6, 1
	v_pk_mul_f32 v[6:7], v[2:3], v[144:145]
	s_nop 0
	v_fma_f32 v4, v2, s10, -v6
	v_fmac_f32_e32 v4, 0xb102e308, v2
	v_pk_add_f32 v[2:3], v[6:7], v[4:5]
	s_mov_b32 s10, 0x7f800000
	v_sub_f32_e32 v5, v3, v5
	v_sub_f32_e32 v5, v7, v5
	v_add_f32_e32 v9, v8, v5
	v_mov_b32_e32 v8, v6
	v_pk_add_f32 v[6:7], v[2:3], v[6:7] neg_lo:[0,1] neg_hi:[0,1]
	v_pk_add_f32 v[14:15], v[2:3], v[8:9]
	v_mov_b32_e32 v5, v2
	v_mov_b32_e32 v7, v15
	v_pk_add_f32 v[16:17], v[4:5], v[6:7] neg_lo:[0,1] neg_hi:[0,1]
	v_pk_add_f32 v[4:5], v[4:5], v[6:7]
	v_mov_b32_e32 v8, v9
	v_pk_add_f32 v[6:7], v[4:5], v[2:3] op_sel:[1,0] op_sel_hi:[0,1] neg_lo:[0,1] neg_hi:[0,1]
	v_pk_add_f32 v[44:45], v[14:15], v[6:7] op_sel_hi:[1,0] neg_lo:[0,1] neg_hi:[0,1]
	v_mov_b32_e32 v14, v15
	v_mov_b32_e32 v15, v5
	v_pk_mov_b32 v[6:7], v[2:3], v[6:7] op_sel:[1,0]
	v_mov_b32_e32 v9, v2
	v_pk_add_f32 v[6:7], v[14:15], v[6:7] neg_lo:[0,1] neg_hi:[0,1]
	v_mov_b32_e32 v44, v16
	v_pk_add_f32 v[2:3], v[8:9], v[6:7] neg_lo:[0,1] neg_hi:[0,1]
	v_mov_b32_e32 v17, v5
	v_pk_add_f32 v[6:7], v[44:45], v[2:3]
	v_cmp_neq_f32_e64 s[10:11], s10, v11
	v_pk_add_f32 v[8:9], v[6:7], v[6:7] op_sel:[0,1] op_sel_hi:[1,0]
	s_nop 0
	v_pk_add_f32 v[4:5], v[4:5], v[8:9] op_sel:[1,0] op_sel_hi:[0,1]
	v_mov_b32_e32 v7, v4
	v_pk_add_f32 v[14:15], v[6:7], v[16:17] neg_lo:[0,1] neg_hi:[0,1]
	v_mov_b32_e32 v3, v8
	v_sub_f32_e32 v5, v6, v14
	v_pk_add_f32 v[2:3], v[2:3], v[14:15] neg_lo:[0,1] neg_hi:[0,1]
	v_sub_f32_e32 v5, v16, v5
	v_add_f32_e32 v2, v2, v5
	v_add_f32_e32 v2, v2, v3
	v_add_f32_e32 v2, v4, v2
	v_cndmask_b32_e64 v2, v172, v2, s[10:11]
	v_cmp_ngt_f32_e64 s[10:11], -1.0, v11
	s_nop 1
	v_cndmask_b32_e64 v2, v173, v2, s[10:11]
	v_cmp_neq_f32_e64 s[10:11], -1.0, v11
	s_nop 1
	v_cndmask_b32_e64 v2, v163, v2, s[10:11]
	s_mov_b32 s10, 0x33800000
	v_cmp_lt_f32_e64 s[10:11], |v11|, s10
	s_nop 1
	v_cndmask_b32_e64 v2, v2, v11, s[10:11]
